# phase 6: nt hint on the H stores (16-byte row stores, read only after the next grid barrier)
# baseline (speedup 1.0000x reference)
; #define PG8_STAGE(bufoff, gbase, voff) do { _Pragma("unroll") for (int _i = 0; _i < 2; ++_i) \
;         __builtin_amdgcn_global_load_lds((const unsigned*)((const char*)(gbase) + (voff)[_i]), (PG8_LAS unsigned*)(lds + (bufoff) + ldsw + _i * 8192), 16, 0, 0); } while (0)
; #define PG8_LDA(dst, b, h) do { _Pragma("unroll") for (int m = 0; m < 4; ++m) _Pragma("unroll") for (int k = 0; k < 2; ++k) dst[m][k] = *(const PG8_LAS bf16x8*)(lds + PG8_SA(b, h) + aoff + m * 2048 + k * 1024); } while (0)
; #define PG8_LDB(dst, b, h) do { _Pragma("unroll") for (int n = 0; n < 2; ++n) _Pragma("unroll") for (int k = 0; k < 2; ++k) dst[n][k] = *(const PG8_LAS bf16x8*)(lds + PG8_SB(b, h) + boff + n * 2048 + k * 1024); } while (0)
; #define PG8_MMA(ai, bj, At, Bt) do { __builtin_amdgcn_s_setprio(1); _Pragma("unroll") for (int m = 0; m < 4; ++m) _Pragma("unroll") for (int n = 0; n < 2; ++n) _Pragma("unroll") for (int k = 0; k < 2; ++k) \
;         acc[ai][bj][m][n] = __builtin_amdgcn_mfma_f32_16x16x32_bf16(Bt[n][k], At[m][k], acc[ai][bj][m][n], 0, 0, 0); __builtin_amdgcn_s_setprio(0); } while (0)
; #define PG8_WAIT_V(n) asm volatile("s_waitcnt vmcnt(" #n ")" ::: "memory")
; #define PG8_WAIT_L(n) asm volatile("s_waitcnt lgkmcnt(" #n ")" ::: "memory")
; #define PG8_BAR __builtin_amdgcn_s_barrier()
; #define PG8_SCHED __builtin_amdgcn_sched_barrier(0)
; template <class Epi, class Sched>
; __device__ __forceinline__ void gemm_phase(PG8_LAS unsigned char* lds, const Gemm g, const Sched& S, const Epi& E) {
;     ...
;             PG8_LDB(B0, 0, 0); PG8_SCHED; PG8_LDA(At, 0, 0); PG8_STAGE(PG8_SA(1, 1), a1 + hstep, voffA);
;             PG8_WAIT_L(8); PG8_BAR; PG8_WAIT_L(0); PG8_MMA(0, 0, At, B0); PG8_BAR; PG8_SCHED;
;             PG8_LDB(B1, 0, 1); PG8_STAGE(PG8_SB(0, 0), b2, voffB);
;             PG8_BAR; PG8_WAIT_L(0); PG8_MMA(0, 1, At, B1); PG8_BAR;
;             PG8_LDA(At, 0, 1); PG8_STAGE(PG8_SA(0, 0), a2, voffA);
;             PG8_BAR; PG8_WAIT_L(0); PG8_MMA(1, 0, At, B0); PG8_BAR; PG8_SCHED;
;             PG8_STAGE(PG8_SB(0, 1), b2 + hstep, voffB);
;             PG8_WAIT_V(6); PG8_BAR; PG8_MMA(1, 1, At, B1); PG8_BAR;
;             PG8_LDB(B0, 1, 0); PG8_SCHED; PG8_LDA(At, 1, 0); PG8_STAGE(PG8_SA(0, 1), a2 + hstep, voffA);
;             PG8_WAIT_L(8); PG8_BAR; PG8_WAIT_L(0); PG8_MMA(0, 0, At, B0); PG8_BAR; PG8_SCHED;
.LBB0_800:
	ds_read_b128 v[138:141], v145
	ds_read_b128 v[162:165], v146
	ds_read_b128 v[166:169], v147
	ds_read_b128 v[170:173], v148
	s_add_u32 s28, s26, 0xfffc0080
	s_addc_u32 s29, s27, -1
	s_cmp_eq_u32 s58, 12
	s_cselect_b32 s31, s17, s29
	s_cselect_b32 s30, s54, s28
	s_cselect_b32 s29, s15, s57
	s_cselect_b32 s28, s55, s56
	s_mov_b32 m0, s51
	v_lshl_add_u64 v[206:207], s[26:27], 0, v[134:135]
	ds_read_b128 v[174:177], v143
	ds_read_b128 v[178:181], v143 offset:1024
	ds_read_b128 v[182:185], v143 offset:2048
	ds_read_b128 v[186:189], v143 offset:3072
	ds_read_b128 v[190:193], v143 offset:4096
	ds_read_b128 v[194:197], v143 offset:5120
	ds_read_b128 v[198:201], v143 offset:6144
	ds_read_b128 v[202:205], v143 offset:7168
	global_load_lds_dwordx4 v[206:207], off
	v_lshl_add_u64 v[206:207], s[26:27], 0, v[136:137]
	s_mov_b32 m0, s52
	s_nop 0
	global_load_lds_dwordx4 v[206:207], off
	s_waitcnt lgkmcnt(8)
	s_barrier
	s_waitcnt lgkmcnt(0)
	s_setprio 1
	s_waitcnt lgkmcnt(0)
	v_mfma_f32_16x16x32_bf16 v[126:129], v[138:141], v[174:177], v[126:129]
	v_mfma_f32_16x16x32_bf16 v[122:125], v[166:169], v[174:177], v[122:125]
	v_mfma_f32_16x16x32_bf16 v[110:113], v[138:141], v[182:185], v[110:113]
	v_mfma_f32_16x16x32_bf16 v[106:109], v[166:169], v[182:185], v[106:109]
	v_mfma_f32_16x16x32_bf16 v[94:97], v[138:141], v[190:193], v[94:97]
	v_mfma_f32_16x16x32_bf16 v[90:93], v[166:169], v[190:193], v[90:93]
	v_mfma_f32_16x16x32_bf16 v[78:81], v[138:141], v[198:201], v[78:81]
	v_mfma_f32_16x16x32_bf16 v[74:77], v[166:169], v[198:201], v[74:77]
	v_mfma_f32_16x16x32_bf16 v[126:129], v[162:165], v[178:181], v[126:129]
	v_mfma_f32_16x16x32_bf16 v[122:125], v[170:173], v[178:181], v[122:125]
	v_mfma_f32_16x16x32_bf16 v[110:113], v[162:165], v[186:189], v[110:113]
	v_mfma_f32_16x16x32_bf16 v[106:109], v[170:173], v[186:189], v[106:109]
	v_mfma_f32_16x16x32_bf16 v[94:97], v[162:165], v[194:197], v[94:97]
	v_mfma_f32_16x16x32_bf16 v[90:93], v[170:173], v[194:197], v[90:93]
	v_mfma_f32_16x16x32_bf16 v[78:81], v[162:165], v[202:205], v[78:81]
	v_mfma_f32_16x16x32_bf16 v[74:77], v[170:173], v[202:205], v[74:77]
	s_setprio 0
	s_barrier
	s_mov_b32 m0, s23
	v_lshl_add_u64 v[222:223], s[28:29], 0, v[130:131]
	ds_read_b128 v[206:209], v149
	ds_read_b128 v[210:213], v150
	ds_read_b128 v[214:217], v151
	ds_read_b128 v[218:221], v152
	global_load_lds_dwordx4 v[222:223], off
	v_lshl_add_u64 v[224:225], s[28:29], 0, v[132:133]
	s_mov_b32 m0, s25
	s_nop 0
	global_load_lds_dwordx4 v[224:225], off
	s_barrier
	s_waitcnt lgkmcnt(0)
	s_setprio 1
	s_waitcnt lgkmcnt(0)
	v_mfma_f32_16x16x32_bf16 v[118:121], v[206:209], v[174:177], v[118:121]
	v_mfma_f32_16x16x32_bf16 v[114:117], v[214:217], v[174:177], v[114:117]
	v_mfma_f32_16x16x32_bf16 v[102:105], v[206:209], v[182:185], v[102:105]
	v_mfma_f32_16x16x32_bf16 v[98:101], v[214:217], v[182:185], v[98:101]
	v_mfma_f32_16x16x32_bf16 v[86:89], v[206:209], v[190:193], v[86:89]
	v_mfma_f32_16x16x32_bf16 v[82:85], v[214:217], v[190:193], v[82:85]
	v_mfma_f32_16x16x32_bf16 v[70:73], v[206:209], v[198:201], v[70:73]
	v_mfma_f32_16x16x32_bf16 v[66:69], v[214:217], v[198:201], v[66:69]
	v_mfma_f32_16x16x32_bf16 v[118:121], v[210:213], v[178:181], v[118:121]
	v_mfma_f32_16x16x32_bf16 v[114:117], v[218:221], v[178:181], v[114:117]
	v_mfma_f32_16x16x32_bf16 v[102:105], v[210:213], v[186:189], v[102:105]
	v_mfma_f32_16x16x32_bf16 v[98:101], v[218:221], v[186:189], v[98:101]
	v_mfma_f32_16x16x32_bf16 v[86:89], v[210:213], v[194:197], v[86:89]
	v_mfma_f32_16x16x32_bf16 v[82:85], v[218:221], v[194:197], v[82:85]
	v_mfma_f32_16x16x32_bf16 v[70:73], v[210:213], v[202:205], v[70:73]
	v_mfma_f32_16x16x32_bf16 v[66:69], v[218:221], v[202:205], v[66:69]
	s_setprio 0
	s_mov_b32 m0, s38
	v_lshl_add_u64 v[226:227], s[30:31], 0, v[130:131]
	s_barrier
	ds_read_b128 v[174:177], v143 offset:16384
	ds_read_b128 v[178:181], v143 offset:17408
	ds_read_b128 v[182:185], v143 offset:18432
	ds_read_b128 v[186:189], v143 offset:19456
	ds_read_b128 v[190:193], v143 offset:20480
	ds_read_b128 v[194:197], v143 offset:21504
	ds_read_b128 v[198:201], v143 offset:22528
	ds_read_b128 v[202:205], v143 offset:23552
	global_load_lds_dwordx4 v[226:227], off
	v_lshl_add_u64 v[228:229], s[30:31], 0, v[132:133]
	s_mov_b32 m0, s39
	s_nop 0
	global_load_lds_dwordx4 v[228:229], off
	s_barrier
	s_waitcnt lgkmcnt(0)
	s_setprio 1
	s_waitcnt lgkmcnt(0)
	v_mfma_f32_16x16x32_bf16 v[62:65], v[138:141], v[174:177], v[62:65]
	v_mfma_f32_16x16x32_bf16 v[58:61], v[166:169], v[174:177], v[58:61]
	v_mfma_f32_16x16x32_bf16 v[46:49], v[138:141], v[182:185], v[46:49]
	v_mfma_f32_16x16x32_bf16 v[42:45], v[166:169], v[182:185], v[42:45]
	v_mfma_f32_16x16x32_bf16 v[30:33], v[138:141], v[190:193], v[30:33]
	v_mfma_f32_16x16x32_bf16 v[26:29], v[166:169], v[190:193], v[26:29]
	v_mfma_f32_16x16x32_bf16 v[14:17], v[138:141], v[198:201], v[14:17]
	v_mfma_f32_16x16x32_bf16 v[10:13], v[166:169], v[198:201], v[10:13]
	v_mfma_f32_16x16x32_bf16 v[62:65], v[162:165], v[178:181], v[62:65]
	v_mfma_f32_16x16x32_bf16 v[58:61], v[170:173], v[178:181], v[58:61]
	v_mfma_f32_16x16x32_bf16 v[46:49], v[162:165], v[186:189], v[46:49]
	v_mfma_f32_16x16x32_bf16 v[42:45], v[170:173], v[186:189], v[42:45]
	v_mfma_f32_16x16x32_bf16 v[30:33], v[162:165], v[194:197], v[30:33]
	v_mfma_f32_16x16x32_bf16 v[26:29], v[170:173], v[194:197], v[26:29]
	v_mfma_f32_16x16x32_bf16 v[14:17], v[162:165], v[202:205], v[14:17]
	v_mfma_f32_16x16x32_bf16 v[10:13], v[170:173], v[202:205], v[10:13]
	s_setprio 0
	s_barrier
; #define PG8_STAGE(bufoff, gbase, voff) do { _Pragma("unroll") for (int _i = 0; _i < 2; ++_i) \
;         __builtin_amdgcn_global_load_lds((const unsigned*)((const char*)(gbase) + (voff)[_i]), (PG8_LAS unsigned*)(lds + (bufoff) + ldsw + _i * 8192), 16, 0, 0); } while (0)
; #define PG8_LDA(dst, b, h) do { _Pragma("unroll") for (int m = 0; m < 4; ++m) _Pragma("unroll") for (int k = 0; k < 2; ++k) dst[m][k] = *(const PG8_LAS bf16x8*)(lds + PG8_SA(b, h) + aoff + m * 2048 + k * 1024); } while (0)
; #define PG8_LDB(dst, b, h) do { _Pragma("unroll") for (int n = 0; n < 2; ++n) _Pragma("unroll") for (int k = 0; k < 2; ++k) dst[n][k] = *(const PG8_LAS bf16x8*)(lds + PG8_SB(b, h) + boff + n * 2048 + k * 1024); } while (0)
; #define PG8_MMA(ai, bj, At, Bt) do { __builtin_amdgcn_s_setprio(1); _Pragma("unroll") for (int m = 0; m < 4; ++m) _Pragma("unroll") for (int n = 0; n < 2; ++n) _Pragma("unroll") for (int k = 0; k < 2; ++k) \
;         acc[ai][bj][m][n] = __builtin_amdgcn_mfma_f32_16x16x32_bf16(Bt[n][k], At[m][k], acc[ai][bj][m][n], 0, 0, 0); __builtin_amdgcn_s_setprio(0); } while (0)
; #define PG8_WAIT_V(n) asm volatile("s_waitcnt vmcnt(" #n ")" ::: "memory")
; #define PG8_WAIT_L(n) asm volatile("s_waitcnt lgkmcnt(" #n ")" ::: "memory")
; #define PG8_BAR __builtin_amdgcn_s_barrier()
; #define PG8_SCHED __builtin_amdgcn_sched_barrier(0)
; template <class Epi, class Sched>
; __device__ __forceinline__ void gemm_phase(PG8_LAS unsigned char* lds, const Gemm g, const Sched& S, const Epi& E) {
;     ...
;             PG8_STAGE(PG8_SB(0, 1), b2 + hstep, voffB);
;             PG8_WAIT_V(6); PG8_BAR; PG8_MMA(1, 1, At, B1); PG8_BAR;
;             PG8_LDB(B0, 1, 0); PG8_SCHED; PG8_LDA(At, 1, 0); PG8_STAGE(PG8_SA(0, 1), a2 + hstep, voffA);
;             PG8_WAIT_L(8); PG8_BAR; PG8_WAIT_L(0); PG8_MMA(0, 0, At, B0); PG8_BAR; PG8_SCHED;
;             PG8_LDB(B1, 1, 1); PG8_STAGE(PG8_SB(1, 0), b3, voffB);
;             PG8_BAR; PG8_WAIT_L(0); PG8_MMA(0, 1, At, B1); PG8_BAR;
;             PG8_LDA(At, 1, 1); PG8_STAGE(PG8_SA(1, 0), a3, voffA);
;             PG8_BAR; PG8_WAIT_L(0); PG8_MMA(1, 0, At, B0); PG8_BAR; PG8_SCHED;
	s_add_u32 s60, s28, 0x40000
	s_addc_u32 s61, s29, 0
	s_mov_b32 m0, s40
	v_lshl_add_u64 v[138:139], s[60:61], 0, v[130:131]
	global_load_lds_dwordx4 v[138:139], off
	v_lshl_add_u64 v[138:139], s[60:61], 0, v[132:133]
	s_mov_b32 m0, s41
	s_nop 0
	global_load_lds_dwordx4 v[138:139], off
	s_waitcnt vmcnt(6)
	s_barrier
	s_setprio 1
	v_mfma_f32_16x16x32_bf16 v[54:57], v[206:209], v[174:177], v[54:57]
	v_mfma_f32_16x16x32_bf16 v[50:53], v[214:217], v[174:177], v[50:53]
	v_mfma_f32_16x16x32_bf16 v[38:41], v[206:209], v[182:185], v[38:41]
	v_mfma_f32_16x16x32_bf16 v[34:37], v[214:217], v[182:185], v[34:37]
	v_mfma_f32_16x16x32_bf16 v[22:25], v[206:209], v[190:193], v[22:25]
	v_mfma_f32_16x16x32_bf16 v[18:21], v[214:217], v[190:193], v[18:21]
	v_mfma_f32_16x16x32_bf16 v[6:9], v[206:209], v[198:201], v[6:9]
	v_mfma_f32_16x16x32_bf16 v[2:5], v[214:217], v[198:201], v[2:5]
	v_mfma_f32_16x16x32_bf16 v[54:57], v[210:213], v[178:181], v[54:57]
	v_mfma_f32_16x16x32_bf16 v[50:53], v[218:221], v[178:181], v[50:53]
	v_mfma_f32_16x16x32_bf16 v[38:41], v[210:213], v[186:189], v[38:41]
	v_mfma_f32_16x16x32_bf16 v[34:37], v[218:221], v[186:189], v[34:37]
	v_mfma_f32_16x16x32_bf16 v[22:25], v[210:213], v[194:197], v[22:25]
	v_mfma_f32_16x16x32_bf16 v[18:21], v[218:221], v[194:197], v[18:21]
	v_mfma_f32_16x16x32_bf16 v[6:9], v[210:213], v[202:205], v[6:9]
	v_mfma_f32_16x16x32_bf16 v[2:5], v[218:221], v[202:205], v[2:5]
	s_setprio 0
	s_barrier
	ds_read_b128 v[138:141], v153
	ds_read_b128 v[162:165], v154
	ds_read_b128 v[166:169], v155
	ds_read_b128 v[170:173], v156
	s_add_u32 s30, s30, 0x40000
	s_addc_u32 s31, s31, 0
	s_mov_b32 m0, s42
	v_lshl_add_u64 v[206:207], s[30:31], 0, v[130:131]
	ds_read_b128 v[174:177], v143 offset:32768
	ds_read_b128 v[178:181], v143 offset:33792
	ds_read_b128 v[182:185], v143 offset:34816
	ds_read_b128 v[186:189], v143 offset:35840
	ds_read_b128 v[190:193], v143 offset:36864
	ds_read_b128 v[194:197], v143 offset:37888
	ds_read_b128 v[198:201], v143 offset:38912
	ds_read_b128 v[202:205], v143 offset:39936
	global_load_lds_dwordx4 v[206:207], off
	v_lshl_add_u64 v[206:207], s[30:31], 0, v[132:133]
	s_mov_b32 m0, s43
	s_nop 0
	global_load_lds_dwordx4 v[206:207], off
	s_waitcnt lgkmcnt(8)
	s_barrier
	s_waitcnt lgkmcnt(0)
	s_setprio 1
	s_waitcnt lgkmcnt(0)
	v_mfma_f32_16x16x32_bf16 v[126:129], v[138:141], v[174:177], v[126:129]
	v_mfma_f32_16x16x32_bf16 v[122:125], v[166:169], v[174:177], v[122:125]
	v_mfma_f32_16x16x32_bf16 v[110:113], v[138:141], v[182:185], v[110:113]
	v_mfma_f32_16x16x32_bf16 v[106:109], v[166:169], v[182:185], v[106:109]
	v_mfma_f32_16x16x32_bf16 v[94:97], v[138:141], v[190:193], v[94:97]
	v_mfma_f32_16x16x32_bf16 v[90:93], v[166:169], v[190:193], v[90:93]
	v_mfma_f32_16x16x32_bf16 v[78:81], v[138:141], v[198:201], v[78:81]
	v_mfma_f32_16x16x32_bf16 v[74:77], v[166:169], v[198:201], v[74:77]
	v_mfma_f32_16x16x32_bf16 v[126:129], v[162:165], v[178:181], v[126:129]
	v_mfma_f32_16x16x32_bf16 v[122:125], v[170:173], v[178:181], v[122:125]
	v_mfma_f32_16x16x32_bf16 v[110:113], v[162:165], v[186:189], v[110:113]
	v_mfma_f32_16x16x32_bf16 v[106:109], v[170:173], v[186:189], v[106:109]
	v_mfma_f32_16x16x32_bf16 v[94:97], v[162:165], v[194:197], v[94:97]
	v_mfma_f32_16x16x32_bf16 v[90:93], v[170:173], v[194:197], v[90:93]
	v_mfma_f32_16x16x32_bf16 v[78:81], v[162:165], v[202:205], v[78:81]
	v_mfma_f32_16x16x32_bf16 v[74:77], v[170:173], v[202:205], v[74:77]
	s_setprio 0
	s_barrier
	s_mov_b32 m0, s44
	v_lshl_add_u64 v[222:223], v[222:223], 0, s[8:9]
	ds_read_b128 v[206:209], v157
	ds_read_b128 v[210:213], v158
	ds_read_b128 v[214:217], v159
	ds_read_b128 v[218:221], v160
	global_load_lds_dwordx4 v[222:223], off
	v_lshl_add_u64 v[222:223], v[224:225], 0, s[8:9]
	s_mov_b32 m0, s45
	s_nop 0
	global_load_lds_dwordx4 v[222:223], off
	s_barrier
	s_waitcnt lgkmcnt(0)
	s_setprio 1
	s_waitcnt lgkmcnt(0)
	v_mfma_f32_16x16x32_bf16 v[118:121], v[206:209], v[174:177], v[118:121]
	v_mfma_f32_16x16x32_bf16 v[114:117], v[214:217], v[174:177], v[114:117]
	v_mfma_f32_16x16x32_bf16 v[102:105], v[206:209], v[182:185], v[102:105]
	v_mfma_f32_16x16x32_bf16 v[98:101], v[214:217], v[182:185], v[98:101]
	v_mfma_f32_16x16x32_bf16 v[86:89], v[206:209], v[190:193], v[86:89]
	v_mfma_f32_16x16x32_bf16 v[82:85], v[214:217], v[190:193], v[82:85]
	v_mfma_f32_16x16x32_bf16 v[70:73], v[206:209], v[198:201], v[70:73]
	v_mfma_f32_16x16x32_bf16 v[66:69], v[214:217], v[198:201], v[66:69]
	v_mfma_f32_16x16x32_bf16 v[118:121], v[210:213], v[178:181], v[118:121]
	v_mfma_f32_16x16x32_bf16 v[114:117], v[218:221], v[178:181], v[114:117]
	v_mfma_f32_16x16x32_bf16 v[102:105], v[210:213], v[186:189], v[102:105]
	v_mfma_f32_16x16x32_bf16 v[98:101], v[218:221], v[186:189], v[98:101]
	v_mfma_f32_16x16x32_bf16 v[86:89], v[210:213], v[194:197], v[86:89]
	v_mfma_f32_16x16x32_bf16 v[82:85], v[218:221], v[194:197], v[82:85]
	v_mfma_f32_16x16x32_bf16 v[70:73], v[210:213], v[202:205], v[70:73]
	v_mfma_f32_16x16x32_bf16 v[66:69], v[218:221], v[202:205], v[66:69]
	s_setprio 0
	s_mov_b32 m0, s46
	v_lshl_add_u64 v[222:223], v[226:227], 0, s[8:9]
	s_barrier
	ds_read_b128 v[174:177], v143 offset:49152
	ds_read_b128 v[178:181], v143 offset:50176
	ds_read_b128 v[182:185], v143 offset:51200
	ds_read_b128 v[186:189], v143 offset:52224
	ds_read_b128 v[190:193], v143 offset:53248
	ds_read_b128 v[194:197], v143 offset:54272
	ds_read_b128 v[198:201], v143 offset:55296
	ds_read_b128 v[202:205], v143 offset:56320
	global_load_lds_dwordx4 v[222:223], off
	v_lshl_add_u64 v[222:223], v[228:229], 0, s[8:9]
	s_mov_b32 m0, s47
	s_nop 0
	global_load_lds_dwordx4 v[222:223], off
	s_barrier
; #define PG8_STAGE(bufoff, gbase, voff) do { _Pragma("unroll") for (int _i = 0; _i < 2; ++_i) \
;         __builtin_amdgcn_global_load_lds((const unsigned*)((const char*)(gbase) + (voff)[_i]), (PG8_LAS unsigned*)(lds + (bufoff) + ldsw + _i * 8192), 16, 0, 0); } while (0)
; #define PG8_MMA(ai, bj, At, Bt) do { __builtin_amdgcn_s_setprio(1); _Pragma("unroll") for (int m = 0; m < 4; ++m) _Pragma("unroll") for (int n = 0; n < 2; ++n) _Pragma("unroll") for (int k = 0; k < 2; ++k) \
;         acc[ai][bj][m][n] = __builtin_amdgcn_mfma_f32_16x16x32_bf16(Bt[n][k], At[m][k], acc[ai][bj][m][n], 0, 0, 0); __builtin_amdgcn_s_setprio(0); } while (0)
; #define PG8_WAIT_V(n) asm volatile("s_waitcnt vmcnt(" #n ")" ::: "memory")
; #define PG8_WAIT_L(n) asm volatile("s_waitcnt lgkmcnt(" #n ")" ::: "memory")
; #define PG8_BAR __builtin_amdgcn_s_barrier()
; #define PG8_SCHED __builtin_amdgcn_sched_barrier(0)
; template <class Epi, class Sched>
; __device__ __forceinline__ void gemm_phase(PG8_LAS unsigned char* lds, const Gemm g, const Sched& S, const Epi& E) {
;     ...
;             PG8_BAR; PG8_WAIT_L(0); PG8_MMA(1, 0, At, B0); PG8_BAR; PG8_SCHED;
;             PG8_STAGE(PG8_SB(1, 1), b3 + hstep, voffB);
;             PG8_WAIT_V(6); PG8_BAR; PG8_MMA(1, 1, At, B1); PG8_BAR;
;   __device__ __forceinline__ void operator()(const acc8_t& acc, const pg8::Unit& u, int wr, int wc, int fr, int fq) const {
;     ...
; #pragma unroll
;     for (int ai = 0; ai < 2; ai++)
; #pragma unroll
;       for (int m = 0; m < 4; m++) {
;         const size_t token = EPI_TOKEN(u, ai, m);
;         const float rs = rsqrtf(rss[token] * (1.f / 1024.f) + 1e-6f);
; #pragma unroll
;         for (int bj = 0; bj < 2; bj++)
; #pragma unroll
;           for (int n = 0; n < 2; n++) {
;             const int f = EPI_COL(u, bj, n);
;             const float v0 = fmaxf(acc[ai][bj][m][n][0] * rs, 0.f), v1 = fmaxf(acc[ai][bj][m][n][1] * rs, 0.f);
;             const float v2 = fmaxf(acc[ai][bj][m][n][2] * rs, 0.f), v3 = fmaxf(acc[ai][bj][m][n][3] * rs, 0.f);
;             uint2 o; o.x = pack2(v0 * v0, v1 * v1); o.y = pack2(v2 * v2, v3 * v3);
	s_waitcnt lgkmcnt(0)
	s_setprio 1
	s_waitcnt lgkmcnt(0)
	v_mfma_f32_16x16x32_bf16 v[62:65], v[138:141], v[174:177], v[62:65]
	v_mfma_f32_16x16x32_bf16 v[58:61], v[166:169], v[174:177], v[58:61]
	v_mfma_f32_16x16x32_bf16 v[46:49], v[138:141], v[182:185], v[46:49]
	v_mfma_f32_16x16x32_bf16 v[42:45], v[166:169], v[182:185], v[42:45]
	v_mfma_f32_16x16x32_bf16 v[30:33], v[138:141], v[190:193], v[30:33]
	v_mfma_f32_16x16x32_bf16 v[26:29], v[166:169], v[190:193], v[26:29]
	v_mfma_f32_16x16x32_bf16 v[14:17], v[138:141], v[198:201], v[14:17]
	v_mfma_f32_16x16x32_bf16 v[10:13], v[166:169], v[198:201], v[10:13]
	v_mfma_f32_16x16x32_bf16 v[62:65], v[162:165], v[178:181], v[62:65]
	v_mfma_f32_16x16x32_bf16 v[58:61], v[170:173], v[178:181], v[58:61]
	v_mfma_f32_16x16x32_bf16 v[46:49], v[162:165], v[186:189], v[46:49]
	v_mfma_f32_16x16x32_bf16 v[42:45], v[170:173], v[186:189], v[42:45]
	v_mfma_f32_16x16x32_bf16 v[30:33], v[162:165], v[194:197], v[30:33]
	v_mfma_f32_16x16x32_bf16 v[26:29], v[170:173], v[194:197], v[26:29]
	v_mfma_f32_16x16x32_bf16 v[14:17], v[162:165], v[202:205], v[14:17]
	v_mfma_f32_16x16x32_bf16 v[10:13], v[170:173], v[202:205], v[10:13]
	s_setprio 0
	s_barrier
	s_add_u32 s28, s28, 0x40080
	s_addc_u32 s29, s29, 0
	s_mov_b32 m0, s48
	v_lshl_add_u64 v[138:139], s[28:29], 0, v[130:131]
	global_load_lds_dwordx4 v[138:139], off
	v_lshl_add_u64 v[138:139], s[28:29], 0, v[132:133]
	s_mov_b32 m0, s49
	s_nop 0
	global_load_lds_dwordx4 v[138:139], off
	s_waitcnt vmcnt(6)
	s_barrier
	s_setprio 1
	v_mfma_f32_16x16x32_bf16 v[54:57], v[206:209], v[174:177], v[54:57]
	v_mfma_f32_16x16x32_bf16 v[50:53], v[214:217], v[174:177], v[50:53]
	v_mfma_f32_16x16x32_bf16 v[38:41], v[206:209], v[182:185], v[38:41]
	v_mfma_f32_16x16x32_bf16 v[34:37], v[214:217], v[182:185], v[34:37]
	v_mfma_f32_16x16x32_bf16 v[22:25], v[206:209], v[190:193], v[22:25]
	v_mfma_f32_16x16x32_bf16 v[18:21], v[214:217], v[190:193], v[18:21]
	v_mfma_f32_16x16x32_bf16 v[6:9], v[206:209], v[198:201], v[6:9]
	v_mfma_f32_16x16x32_bf16 v[2:5], v[214:217], v[198:201], v[2:5]
	v_mfma_f32_16x16x32_bf16 v[54:57], v[210:213], v[178:181], v[54:57]
	v_mfma_f32_16x16x32_bf16 v[50:53], v[218:221], v[178:181], v[50:53]
	v_mfma_f32_16x16x32_bf16 v[38:41], v[210:213], v[186:189], v[38:41]
	v_mfma_f32_16x16x32_bf16 v[34:37], v[218:221], v[186:189], v[34:37]
	v_mfma_f32_16x16x32_bf16 v[22:25], v[210:213], v[194:197], v[22:25]
	v_mfma_f32_16x16x32_bf16 v[18:21], v[218:221], v[194:197], v[18:21]
	v_mfma_f32_16x16x32_bf16 v[6:9], v[210:213], v[202:205], v[6:9]
	v_mfma_f32_16x16x32_bf16 v[2:5], v[218:221], v[202:205], v[2:5]
	s_setprio 0
	s_add_i32 s58, s58, 2
	s_add_u32 s26, s26, 0x100
	s_addc_u32 s27, s27, 0
	s_add_u32 s56, s56, 0x100
	s_addc_u32 s57, s57, 0
	s_cmp_gt_u32 s58, 13
	s_barrier
	s_cbranch_scc0 .LBB0_800
	v_lshl_add_u32 v140, s24, 8, v142
	v_ashrrev_i32_e32 v141, 31, v140
	v_lshl_add_u64 v[138:139], v[140:141], 2, s[12:13]
	global_load_dword v166, v[138:139], off
	global_load_dword v176, v[138:139], off offset:64
	global_load_dword v177, v[138:139], off offset:128
	global_load_dword v178, v[138:139], off offset:192
	global_load_dword v179, v[138:139], off offset:512
	global_load_dword v180, v[138:139], off offset:576
	global_load_dword v181, v[138:139], off offset:640
	global_load_dword v182, v[138:139], off offset:704
	v_lshlrev_b64 v[164:165], 13, v[140:141]
	v_lshl_or_b32 v138, s22, 8, v144
	v_ashrrev_i32_e32 v139, 31, v138
	v_or_b32_e32 v162, 16, v140
	v_lshlrev_b64 v[138:139], 1, v[138:139]
	v_bfe_u32 v230, v0, 4, 1
	v_mul_u32_u24_e32 v230, 24, v230
	v_add_u32_e32 v138, v138, v230
	v_lshl_add_u64 v[164:165], s[10:11], 0, v[164:165]
	v_ashrrev_i32_e32 v163, 31, v162
	v_lshl_add_u64 v[164:165], v[164:165], 0, v[138:139]
	s_mov_b32 s22, s14
	s_mov_b32 s24, s16
	s_mov_b64 s[28:29], s[20:21]
	s_mov_b64 s[26:27], s[18:19]
	s_waitcnt vmcnt(0)
	v_fmamk_f32 v141, v166, 0x3a800000, v161
	v_mul_f32_e32 v166, 0x4b800000, v141
	v_cmp_gt_f32_e32 vcc, s53, v141
	s_nop 1
	v_cndmask_b32_e32 v141, v141, v166, vcc
	v_rsq_f32_e32 v141, v141
	v_lshl_add_u64 v[166:167], v[162:163], 2, s[12:13]
	v_mul_f32_e32 v168, 0x45800000, v141
	v_cndmask_b32_e32 v141, v141, v168, vcc
	v_mul_f32_e32 v126, v126, v141
	v_mul_f32_e32 v127, v127, v141
	v_mul_f32_e32 v128, v128, v141
	v_mul_f32_e32 v129, v129, v141
	v_mul_f32_e32 v122, v122, v141
	v_mul_f32_e32 v123, v123, v141
	v_mul_f32_e32 v124, v124, v141
	v_mul_f32_e32 v125, v125, v141
	v_mul_f32_e32 v168, v118, v141
	v_mul_f32_e32 v169, v119, v141
	v_mul_f32_e32 v170, v120, v141
	v_mul_f32_e32 v171, v121, v141
	v_mul_f32_e32 v172, v114, v141
	v_mul_f32_e32 v173, v115, v141
	v_mul_f32_e32 v174, v116, v141
	v_mul_f32_e32 v141, v117, v141
	v_max_f32_e32 v114, 0, v126
	v_max_f32_e32 v115, 0, v127
	v_max_f32_e32 v116, 0, v128
	v_max_f32_e32 v117, 0, v129
	v_max_f32_e32 v118, 0, v122
	v_max_f32_e32 v119, 0, v123
	v_max_f32_e32 v120, 0, v124
	v_max_f32_e32 v121, 0, v125
	v_max_f32_e32 v122, 0, v168
	v_max_f32_e32 v123, 0, v169
	v_max_f32_e32 v124, 0, v170
	v_max_f32_e32 v125, 0, v171
	v_max_f32_e32 v126, 0, v172
	v_max_f32_e32 v127, 0, v173
	v_max_f32_e32 v128, 0, v174
	v_max_f32_e32 v129, 0, v141
	v_pk_mul_f32 v[114:115], v[114:115], v[114:115]
	v_pk_mul_f32 v[116:117], v[116:117], v[116:117]
	v_pk_mul_f32 v[118:119], v[118:119], v[118:119]
	v_pk_mul_f32 v[120:121], v[120:121], v[120:121]
	v_pk_mul_f32 v[122:123], v[122:123], v[122:123]
	v_pk_mul_f32 v[124:125], v[124:125], v[124:125]
	v_pk_mul_f32 v[126:127], v[126:127], v[126:127]
	v_pk_mul_f32 v[128:129], v[128:129], v[128:129]
	v_cvt_pk_bf16_f32 v114, v114, v115
	v_cvt_pk_bf16_f32 v115, v116, v117
	v_cvt_pk_bf16_f32 v116, v118, v119
;   __device__ __forceinline__ void operator()(const acc8_t& acc, const pg8::Unit& u, int wr, int wc, int fr, int fq) const {
;     ...
;     for (int ai = 0; ai < 2; ai++)
; #pragma unroll
;       for (int m = 0; m < 4; m++) {
;         const size_t token = EPI_TOKEN(u, ai, m);
;         const float rs = rsqrtf(rss[token] * (1.f / 1024.f) + 1e-6f);
; #pragma unroll
;         for (int bj = 0; bj < 2; bj++)
; #pragma unroll
;           for (int n = 0; n < 2; n++) {
;             const int f = EPI_COL(u, bj, n);
;             const float v0 = fmaxf(acc[ai][bj][m][n][0] * rs, 0.f), v1 = fmaxf(acc[ai][bj][m][n][1] * rs, 0.f);
;             const float v2 = fmaxf(acc[ai][bj][m][n][2] * rs, 0.f), v3 = fmaxf(acc[ai][bj][m][n][3] * rs, 0.f);
;             uint2 o; o.x = pack2(v0 * v0, v1 * v1); o.y = pack2(v2 * v2, v3 * v3);
;             *(uint2*)(H + token * 4096 + f) = o;
	v_cvt_pk_bf16_f32 v117, v120, v121
	v_cvt_pk_bf16_f32 v118, v122, v123
	v_cvt_pk_bf16_f32 v119, v124, v125
	v_cvt_pk_bf16_f32 v120, v126, v127
	v_cvt_pk_bf16_f32 v121, v128, v129
	v_permlane16_swap_b32_e32 v114, v116
	v_permlane16_swap_b32_e32 v115, v117
	v_permlane16_swap_b32_e32 v118, v120
	v_permlane16_swap_b32_e32 v119, v121
	global_store_dwordx4 v[164:165], v[114:117], off nt
	global_store_dwordx4 v[164:165], v[118:121], off offset:256 nt
	s_nop 1
	v_mov_b32_e32 v118, v176
	v_lshlrev_b64 v[116:117], 13, v[162:163]
	v_or_b32_e32 v114, 32, v140
	v_lshl_add_u64 v[116:117], s[10:11], 0, v[116:117]
	v_ashrrev_i32_e32 v115, 31, v114
	v_lshl_add_u64 v[116:117], v[116:117], 0, v[138:139]
	v_fmamk_f32 v118, v118, 0x3a800000, v161
	v_mul_f32_e32 v119, 0x4b800000, v118
	v_cmp_gt_f32_e32 vcc, s53, v118
	s_nop 1
	v_cndmask_b32_e32 v118, v118, v119, vcc
	v_rsq_f32_e32 v120, v118
	v_lshl_add_u64 v[118:119], v[114:115], 2, s[12:13]
	v_mul_f32_e32 v121, 0x45800000, v120
	v_cndmask_b32_e32 v120, v120, v121, vcc
	v_mul_f32_e32 v110, v110, v120
	v_mul_f32_e32 v111, v111, v120
	v_mul_f32_e32 v112, v112, v120
	v_mul_f32_e32 v113, v113, v120
	v_mul_f32_e32 v106, v106, v120
	v_mul_f32_e32 v107, v107, v120
	v_mul_f32_e32 v108, v108, v120
	v_mul_f32_e32 v109, v109, v120
	v_mul_f32_e32 v121, v102, v120
	v_mul_f32_e32 v122, v103, v120
	v_mul_f32_e32 v123, v104, v120
	v_mul_f32_e32 v124, v105, v120
	v_mul_f32_e32 v125, v98, v120
	v_mul_f32_e32 v126, v99, v120
	v_mul_f32_e32 v127, v100, v120
	v_mul_f32_e32 v120, v101, v120
	v_max_f32_e32 v98, 0, v110
	v_max_f32_e32 v99, 0, v111
	v_max_f32_e32 v100, 0, v112
	v_max_f32_e32 v101, 0, v113
	v_max_f32_e32 v102, 0, v106
	v_max_f32_e32 v103, 0, v107
	v_max_f32_e32 v104, 0, v108
	v_max_f32_e32 v105, 0, v109
	v_max_f32_e32 v106, 0, v121
	v_max_f32_e32 v107, 0, v122
	v_max_f32_e32 v108, 0, v123
	v_max_f32_e32 v109, 0, v124
	v_max_f32_e32 v110, 0, v125
	v_max_f32_e32 v111, 0, v126
	v_max_f32_e32 v112, 0, v127
	v_max_f32_e32 v113, 0, v120
	v_pk_mul_f32 v[98:99], v[98:99], v[98:99]
	v_pk_mul_f32 v[100:101], v[100:101], v[100:101]
	v_pk_mul_f32 v[102:103], v[102:103], v[102:103]
	v_pk_mul_f32 v[104:105], v[104:105], v[104:105]
	v_pk_mul_f32 v[106:107], v[106:107], v[106:107]
	v_pk_mul_f32 v[108:109], v[108:109], v[108:109]
	v_pk_mul_f32 v[110:111], v[110:111], v[110:111]
	v_pk_mul_f32 v[112:113], v[112:113], v[112:113]
	v_cvt_pk_bf16_f32 v98, v98, v99
	v_cvt_pk_bf16_f32 v99, v100, v101
	v_cvt_pk_bf16_f32 v100, v102, v103
	v_cvt_pk_bf16_f32 v101, v104, v105
	v_cvt_pk_bf16_f32 v102, v106, v107
	v_cvt_pk_bf16_f32 v103, v108, v109
	v_cvt_pk_bf16_f32 v104, v110, v111
	v_cvt_pk_bf16_f32 v105, v112, v113
	v_permlane16_swap_b32_e32 v98, v100
	v_permlane16_swap_b32_e32 v99, v101
	v_permlane16_swap_b32_e32 v102, v104
	v_permlane16_swap_b32_e32 v103, v105
	global_store_dwordx4 v[116:117], v[98:101], off nt
	global_store_dwordx4 v[116:117], v[102:105], off offset:256 nt
	s_nop 1
	v_mov_b32_e32 v102, v177
	v_lshlrev_b64 v[100:101], 13, v[114:115]
	v_or_b32_e32 v98, 48, v140
	v_lshl_add_u64 v[100:101], s[10:11], 0, v[100:101]
	v_ashrrev_i32_e32 v99, 31, v98
	v_lshl_add_u64 v[100:101], v[100:101], 0, v[138:139]
	v_fmamk_f32 v102, v102, 0x3a800000, v161
	v_mul_f32_e32 v103, 0x4b800000, v102
	v_cmp_gt_f32_e32 vcc, s53, v102
	s_nop 1
	v_cndmask_b32_e32 v102, v102, v103, vcc
	v_rsq_f32_e32 v104, v102
	v_lshl_add_u64 v[102:103], v[98:99], 2, s[12:13]
	v_mul_f32_e32 v105, 0x45800000, v104
	v_cndmask_b32_e32 v104, v104, v105, vcc
	v_mul_f32_e32 v94, v94, v104
	v_mul_f32_e32 v95, v95, v104
	v_mul_f32_e32 v96, v96, v104
	v_mul_f32_e32 v97, v97, v104
	v_mul_f32_e32 v90, v90, v104
	v_mul_f32_e32 v91, v91, v104
	v_mul_f32_e32 v92, v92, v104
	v_mul_f32_e32 v93, v93, v104
	v_mul_f32_e32 v105, v86, v104
	v_mul_f32_e32 v106, v87, v104
	v_mul_f32_e32 v107, v88, v104
	v_mul_f32_e32 v108, v89, v104
	v_mul_f32_e32 v109, v82, v104
	v_mul_f32_e32 v110, v83, v104
	v_mul_f32_e32 v111, v84, v104
	v_mul_f32_e32 v104, v85, v104
	v_max_f32_e32 v82, 0, v94
	v_max_f32_e32 v83, 0, v95
	v_max_f32_e32 v84, 0, v96
	v_max_f32_e32 v85, 0, v97
	v_max_f32_e32 v86, 0, v90
	v_max_f32_e32 v87, 0, v91
	v_max_f32_e32 v88, 0, v92
	v_max_f32_e32 v89, 0, v93
	v_max_f32_e32 v90, 0, v105
	v_max_f32_e32 v91, 0, v106
	v_max_f32_e32 v92, 0, v107
	v_max_f32_e32 v93, 0, v108
	v_max_f32_e32 v94, 0, v109
	v_max_f32_e32 v95, 0, v110
	v_max_f32_e32 v96, 0, v111
	v_max_f32_e32 v97, 0, v104
	v_pk_mul_f32 v[82:83], v[82:83], v[82:83]
	v_pk_mul_f32 v[84:85], v[84:85], v[84:85]
	v_pk_mul_f32 v[86:87], v[86:87], v[86:87]
	v_pk_mul_f32 v[88:89], v[88:89], v[88:89]
	v_pk_mul_f32 v[90:91], v[90:91], v[90:91]
	v_pk_mul_f32 v[92:93], v[92:93], v[92:93]
	v_pk_mul_f32 v[94:95], v[94:95], v[94:95]
	v_pk_mul_f32 v[96:97], v[96:97], v[96:97]
	v_cvt_pk_bf16_f32 v82, v82, v83
	v_cvt_pk_bf16_f32 v83, v84, v85
	v_cvt_pk_bf16_f32 v84, v86, v87
	v_cvt_pk_bf16_f32 v85, v88, v89
	v_cvt_pk_bf16_f32 v86, v90, v91
	v_cvt_pk_bf16_f32 v87, v92, v93
	v_cvt_pk_bf16_f32 v88, v94, v95
	v_cvt_pk_bf16_f32 v89, v96, v97
	v_permlane16_swap_b32_e32 v82, v84
	v_permlane16_swap_b32_e32 v83, v85
	v_permlane16_swap_b32_e32 v86, v88
	v_permlane16_swap_b32_e32 v87, v89
	global_store_dwordx4 v[100:101], v[82:85], off nt
	global_store_dwordx4 v[100:101], v[86:89], off offset:256 nt
	s_nop 1
	v_mov_b32_e32 v86, v178
	v_lshlrev_b64 v[84:85], 13, v[98:99]
	v_add_u32_e32 v82, 0x80, v140
	v_lshl_add_u64 v[84:85], s[10:11], 0, v[84:85]
	v_ashrrev_i32_e32 v83, 31, v82
	v_lshl_add_u64 v[84:85], v[84:85], 0, v[138:139]
	v_fmamk_f32 v86, v86, 0x3a800000, v161
	v_mul_f32_e32 v87, 0x4b800000, v86
	v_cmp_gt_f32_e32 vcc, s53, v86
	s_nop 1
;   __device__ __forceinline__ void operator()(const acc8_t& acc, const pg8::Unit& u, int wr, int wc, int fr, int fq) const {
;     ...
;     for (int ai = 0; ai < 2; ai++)
; #pragma unroll
;       for (int m = 0; m < 4; m++) {
;         const size_t token = EPI_TOKEN(u, ai, m);
;         const float rs = rsqrtf(rss[token] * (1.f / 1024.f) + 1e-6f);
; #pragma unroll
;         for (int bj = 0; bj < 2; bj++)
; #pragma unroll
;           for (int n = 0; n < 2; n++) {
;             const int f = EPI_COL(u, bj, n);
;             const float v0 = fmaxf(acc[ai][bj][m][n][0] * rs, 0.f), v1 = fmaxf(acc[ai][bj][m][n][1] * rs, 0.f);
;             const float v2 = fmaxf(acc[ai][bj][m][n][2] * rs, 0.f), v3 = fmaxf(acc[ai][bj][m][n][3] * rs, 0.f);
;             uint2 o; o.x = pack2(v0 * v0, v1 * v1); o.y = pack2(v2 * v2, v3 * v3);
;             *(uint2*)(H + token * 4096 + f) = o;
	v_cndmask_b32_e32 v86, v86, v87, vcc
	v_rsq_f32_e32 v88, v86
	v_lshl_add_u64 v[86:87], v[82:83], 2, s[12:13]
	v_mul_f32_e32 v89, 0x45800000, v88
	v_cndmask_b32_e32 v88, v88, v89, vcc
	v_mul_f32_e32 v78, v78, v88
	v_mul_f32_e32 v79, v79, v88
	v_mul_f32_e32 v80, v80, v88
	v_mul_f32_e32 v81, v81, v88
	v_mul_f32_e32 v74, v74, v88
	v_mul_f32_e32 v75, v75, v88
	v_mul_f32_e32 v76, v76, v88
	v_mul_f32_e32 v77, v77, v88
	v_mul_f32_e32 v89, v70, v88
	v_mul_f32_e32 v90, v71, v88
	v_mul_f32_e32 v91, v72, v88
	v_mul_f32_e32 v92, v73, v88
	v_mul_f32_e32 v93, v66, v88
	v_mul_f32_e32 v94, v67, v88
	v_mul_f32_e32 v95, v68, v88
	v_mul_f32_e32 v88, v69, v88
	v_max_f32_e32 v66, 0, v78
	v_max_f32_e32 v67, 0, v79
	v_max_f32_e32 v68, 0, v80
	v_max_f32_e32 v69, 0, v81
	v_max_f32_e32 v70, 0, v74
	v_max_f32_e32 v71, 0, v75
	v_max_f32_e32 v72, 0, v76
	v_max_f32_e32 v73, 0, v77
	v_max_f32_e32 v74, 0, v89
	v_max_f32_e32 v75, 0, v90
	v_max_f32_e32 v76, 0, v91
	v_max_f32_e32 v77, 0, v92
	v_max_f32_e32 v78, 0, v93
	v_max_f32_e32 v79, 0, v94
	v_max_f32_e32 v80, 0, v95
	v_max_f32_e32 v81, 0, v88
	v_pk_mul_f32 v[66:67], v[66:67], v[66:67]
	v_pk_mul_f32 v[68:69], v[68:69], v[68:69]
	v_pk_mul_f32 v[70:71], v[70:71], v[70:71]
	v_pk_mul_f32 v[72:73], v[72:73], v[72:73]
	v_pk_mul_f32 v[74:75], v[74:75], v[74:75]
	v_pk_mul_f32 v[76:77], v[76:77], v[76:77]
	v_pk_mul_f32 v[78:79], v[78:79], v[78:79]
	v_pk_mul_f32 v[80:81], v[80:81], v[80:81]
	v_cvt_pk_bf16_f32 v66, v66, v67
	v_cvt_pk_bf16_f32 v67, v68, v69
	v_cvt_pk_bf16_f32 v68, v70, v71
	v_cvt_pk_bf16_f32 v69, v72, v73
	v_cvt_pk_bf16_f32 v70, v74, v75
	v_cvt_pk_bf16_f32 v71, v76, v77
	v_cvt_pk_bf16_f32 v72, v78, v79
	v_cvt_pk_bf16_f32 v73, v80, v81
	v_permlane16_swap_b32_e32 v66, v68
	v_permlane16_swap_b32_e32 v67, v69
	v_permlane16_swap_b32_e32 v70, v72
	v_permlane16_swap_b32_e32 v71, v73
	global_store_dwordx4 v[84:85], v[66:69], off nt
	global_store_dwordx4 v[84:85], v[70:73], off offset:256 nt
	s_nop 1
	v_mov_b32_e32 v70, v179
	v_lshlrev_b64 v[68:69], 13, v[82:83]
	v_add_u32_e32 v66, 0x90, v140
	v_lshl_add_u64 v[68:69], s[10:11], 0, v[68:69]
	v_ashrrev_i32_e32 v67, 31, v66
	v_lshl_add_u64 v[68:69], v[68:69], 0, v[138:139]
	v_fmamk_f32 v70, v70, 0x3a800000, v161
	v_mul_f32_e32 v71, 0x4b800000, v70
	v_cmp_gt_f32_e32 vcc, s53, v70
	s_nop 1
	v_cndmask_b32_e32 v70, v70, v71, vcc
	v_rsq_f32_e32 v72, v70
	v_lshl_add_u64 v[70:71], v[66:67], 2, s[12:13]
	v_mul_f32_e32 v73, 0x45800000, v72
	v_cndmask_b32_e32 v72, v72, v73, vcc
	v_mul_f32_e32 v62, v62, v72
	v_mul_f32_e32 v63, v63, v72
	v_mul_f32_e32 v64, v64, v72
	v_mul_f32_e32 v65, v65, v72
	v_mul_f32_e32 v58, v58, v72
	v_mul_f32_e32 v59, v59, v72
	v_mul_f32_e32 v60, v60, v72
	v_mul_f32_e32 v61, v61, v72
	v_mul_f32_e32 v73, v54, v72
	v_mul_f32_e32 v74, v55, v72
	v_mul_f32_e32 v75, v56, v72
	v_mul_f32_e32 v76, v57, v72
	v_mul_f32_e32 v77, v50, v72
	v_mul_f32_e32 v78, v51, v72
	v_mul_f32_e32 v79, v52, v72
	v_mul_f32_e32 v72, v53, v72
	v_max_f32_e32 v50, 0, v62
	v_max_f32_e32 v51, 0, v63
	v_max_f32_e32 v52, 0, v64
	v_max_f32_e32 v53, 0, v65
	v_max_f32_e32 v54, 0, v58
	v_max_f32_e32 v55, 0, v59
	v_max_f32_e32 v56, 0, v60
	v_max_f32_e32 v57, 0, v61
	v_max_f32_e32 v58, 0, v73
	v_max_f32_e32 v59, 0, v74
	v_max_f32_e32 v60, 0, v75
	v_max_f32_e32 v61, 0, v76
	v_max_f32_e32 v62, 0, v77
	v_max_f32_e32 v63, 0, v78
	v_max_f32_e32 v64, 0, v79
	v_max_f32_e32 v65, 0, v72
	v_pk_mul_f32 v[50:51], v[50:51], v[50:51]
	v_pk_mul_f32 v[52:53], v[52:53], v[52:53]
	v_pk_mul_f32 v[54:55], v[54:55], v[54:55]
	v_pk_mul_f32 v[56:57], v[56:57], v[56:57]
	v_pk_mul_f32 v[58:59], v[58:59], v[58:59]
	v_pk_mul_f32 v[60:61], v[60:61], v[60:61]
	v_pk_mul_f32 v[62:63], v[62:63], v[62:63]
	v_pk_mul_f32 v[64:65], v[64:65], v[64:65]
	v_cvt_pk_bf16_f32 v50, v50, v51
	v_cvt_pk_bf16_f32 v51, v52, v53
	v_cvt_pk_bf16_f32 v52, v54, v55
	v_cvt_pk_bf16_f32 v53, v56, v57
	v_cvt_pk_bf16_f32 v54, v58, v59
	v_cvt_pk_bf16_f32 v55, v60, v61
	v_cvt_pk_bf16_f32 v56, v62, v63
	v_cvt_pk_bf16_f32 v57, v64, v65
	v_permlane16_swap_b32_e32 v50, v52
	v_permlane16_swap_b32_e32 v51, v53
	v_permlane16_swap_b32_e32 v54, v56
	v_permlane16_swap_b32_e32 v55, v57
	global_store_dwordx4 v[68:69], v[50:53], off nt
	global_store_dwordx4 v[68:69], v[54:57], off offset:256 nt
	s_nop 1
	v_mov_b32_e32 v54, v180
	v_lshlrev_b64 v[52:53], 13, v[66:67]
	v_add_u32_e32 v50, 0xa0, v140
	v_lshl_add_u64 v[52:53], s[10:11], 0, v[52:53]
	v_ashrrev_i32_e32 v51, 31, v50
	v_lshl_add_u64 v[52:53], v[52:53], 0, v[138:139]
	v_fmamk_f32 v54, v54, 0x3a800000, v161
	v_mul_f32_e32 v55, 0x4b800000, v54
	v_cmp_gt_f32_e32 vcc, s53, v54
	s_nop 1
	v_cndmask_b32_e32 v54, v54, v55, vcc
	v_rsq_f32_e32 v56, v54
	v_lshl_add_u64 v[54:55], v[50:51], 2, s[12:13]
	v_mul_f32_e32 v57, 0x45800000, v56
	v_cndmask_b32_e32 v56, v56, v57, vcc
	v_mul_f32_e32 v46, v46, v56
	v_mul_f32_e32 v47, v47, v56
	v_mul_f32_e32 v48, v48, v56
	v_mul_f32_e32 v49, v49, v56
	v_mul_f32_e32 v42, v42, v56
	v_mul_f32_e32 v43, v43, v56
	v_mul_f32_e32 v44, v44, v56
	v_mul_f32_e32 v45, v45, v56
	v_mul_f32_e32 v57, v38, v56
	v_mul_f32_e32 v58, v39, v56
	v_mul_f32_e32 v59, v40, v56
	v_mul_f32_e32 v60, v41, v56
	v_mul_f32_e32 v61, v34, v56
	v_mul_f32_e32 v62, v35, v56
	v_mul_f32_e32 v63, v36, v56
	v_mul_f32_e32 v56, v37, v56
	v_max_f32_e32 v34, 0, v46
	v_max_f32_e32 v35, 0, v47
	v_max_f32_e32 v36, 0, v48
	v_max_f32_e32 v37, 0, v49
	v_max_f32_e32 v38, 0, v42
	v_max_f32_e32 v39, 0, v43
	v_max_f32_e32 v40, 0, v44
	v_max_f32_e32 v41, 0, v45
	v_max_f32_e32 v42, 0, v57
	v_max_f32_e32 v43, 0, v58
	v_max_f32_e32 v44, 0, v59
; #define PG8_WAIT_V(n) asm volatile("s_waitcnt vmcnt(" #n ")" ::: "memory")
; #define PG8_BAR __builtin_amdgcn_s_barrier()
; template <class Epi, class Sched>
; __device__ __forceinline__ void gemm_phase(PG8_LAS unsigned char* lds, const Gemm g, const Sched& S, const Epi& E) {
;     ...
;         E(acc, cur, wr, wc, fr, fq);
;         if (!has_next) break;
; #pragma unroll
;         for (int a = 0; a < 2; ++a)
; #pragma unroll
;             for (int b = 0; b < 2; ++b)
; #pragma unroll
;                 for (int m = 0; m < 4; ++m)
; #pragma unroll
;                     for (int n = 0; n < 2; ++n) acc[a][b][m][n] = (f32x4){0.f, 0.f, 0.f, 0.f};
;         cur = nxt; cA = nA; cB = nB; ++ui;
;     }
;     PG8_WAIT_V(0);
;     if (wr == 0) PG8_BAR;
;     PG8_BAR;
;   __device__ __forceinline__ void operator()(const acc8_t& acc, const pg8::Unit& u, int wr, int wc, int fr, int fq) const {
;     ...
;     for (int ai = 0; ai < 2; ai++)
; #pragma unroll
;       for (int m = 0; m < 4; m++) {
;         const size_t token = EPI_TOKEN(u, ai, m);
;         const float rs = rsqrtf(rss[token] * (1.f / 1024.f) + 1e-6f);
; #pragma unroll
;         for (int bj = 0; bj < 2; bj++)
; #pragma unroll
;           for (int n = 0; n < 2; n++) {
;             const int f = EPI_COL(u, bj, n);
;             const float v0 = fmaxf(acc[ai][bj][m][n][0] * rs, 0.f), v1 = fmaxf(acc[ai][bj][m][n][1] * rs, 0.f);
;             const float v2 = fmaxf(acc[ai][bj][m][n][2] * rs, 0.f), v3 = fmaxf(acc[ai][bj][m][n][3] * rs, 0.f);
;             uint2 o; o.x = pack2(v0 * v0, v1 * v1); o.y = pack2(v2 * v2, v3 * v3);
;             *(uint2*)(H + token * 4096 + f) = o;
	v_max_f32_e32 v45, 0, v60
	v_max_f32_e32 v46, 0, v61
	v_max_f32_e32 v47, 0, v62
	v_max_f32_e32 v48, 0, v63
	v_max_f32_e32 v49, 0, v56
	v_pk_mul_f32 v[34:35], v[34:35], v[34:35]
	v_pk_mul_f32 v[36:37], v[36:37], v[36:37]
	v_pk_mul_f32 v[38:39], v[38:39], v[38:39]
	v_pk_mul_f32 v[40:41], v[40:41], v[40:41]
	v_pk_mul_f32 v[42:43], v[42:43], v[42:43]
	v_pk_mul_f32 v[44:45], v[44:45], v[44:45]
	v_pk_mul_f32 v[46:47], v[46:47], v[46:47]
	v_pk_mul_f32 v[48:49], v[48:49], v[48:49]
	v_cvt_pk_bf16_f32 v34, v34, v35
	v_cvt_pk_bf16_f32 v35, v36, v37
	v_cvt_pk_bf16_f32 v36, v38, v39
	v_cvt_pk_bf16_f32 v37, v40, v41
	v_cvt_pk_bf16_f32 v38, v42, v43
	v_cvt_pk_bf16_f32 v39, v44, v45
	v_cvt_pk_bf16_f32 v40, v46, v47
	v_cvt_pk_bf16_f32 v41, v48, v49
	v_permlane16_swap_b32_e32 v34, v36
	v_permlane16_swap_b32_e32 v35, v37
	v_permlane16_swap_b32_e32 v38, v40
	v_permlane16_swap_b32_e32 v39, v41
	global_store_dwordx4 v[52:53], v[34:37], off nt
	global_store_dwordx4 v[52:53], v[38:41], off offset:256 nt
	s_nop 1
	v_mov_b32_e32 v38, v181
	v_lshlrev_b64 v[36:37], 13, v[50:51]
	v_add_u32_e32 v34, 0xb0, v140
	v_lshl_add_u64 v[36:37], s[10:11], 0, v[36:37]
	v_ashrrev_i32_e32 v35, 31, v34
	v_lshl_add_u64 v[36:37], v[36:37], 0, v[138:139]
	v_fmamk_f32 v38, v38, 0x3a800000, v161
	v_mul_f32_e32 v39, 0x4b800000, v38
	v_cmp_gt_f32_e32 vcc, s53, v38
	s_nop 1
	v_cndmask_b32_e32 v38, v38, v39, vcc
	v_rsq_f32_e32 v40, v38
	v_lshl_add_u64 v[38:39], v[34:35], 2, s[12:13]
	v_mul_f32_e32 v41, 0x45800000, v40
	v_cndmask_b32_e32 v40, v40, v41, vcc
	v_mul_f32_e32 v30, v30, v40
	v_mul_f32_e32 v31, v31, v40
	v_mul_f32_e32 v32, v32, v40
	v_mul_f32_e32 v33, v33, v40
	v_mul_f32_e32 v26, v26, v40
	v_mul_f32_e32 v27, v27, v40
	v_mul_f32_e32 v28, v28, v40
	v_mul_f32_e32 v29, v29, v40
	v_mul_f32_e32 v41, v22, v40
	v_mul_f32_e32 v42, v23, v40
	v_mul_f32_e32 v43, v24, v40
	v_mul_f32_e32 v44, v25, v40
	v_mul_f32_e32 v45, v18, v40
	v_mul_f32_e32 v46, v19, v40
	v_mul_f32_e32 v47, v20, v40
	v_mul_f32_e32 v40, v21, v40
	v_max_f32_e32 v18, 0, v30
	v_max_f32_e32 v19, 0, v31
	v_max_f32_e32 v20, 0, v32
	v_max_f32_e32 v21, 0, v33
	v_max_f32_e32 v22, 0, v26
	v_max_f32_e32 v23, 0, v27
	v_max_f32_e32 v24, 0, v28
	v_max_f32_e32 v25, 0, v29
	v_max_f32_e32 v26, 0, v41
	v_max_f32_e32 v27, 0, v42
	v_max_f32_e32 v28, 0, v43
	v_max_f32_e32 v29, 0, v44
	v_max_f32_e32 v30, 0, v45
	v_max_f32_e32 v31, 0, v46
	v_max_f32_e32 v32, 0, v47
	v_max_f32_e32 v33, 0, v40
	v_pk_mul_f32 v[18:19], v[18:19], v[18:19]
	v_pk_mul_f32 v[20:21], v[20:21], v[20:21]
	v_pk_mul_f32 v[22:23], v[22:23], v[22:23]
	v_pk_mul_f32 v[24:25], v[24:25], v[24:25]
	v_pk_mul_f32 v[26:27], v[26:27], v[26:27]
	v_pk_mul_f32 v[28:29], v[28:29], v[28:29]
	v_pk_mul_f32 v[30:31], v[30:31], v[30:31]
	v_pk_mul_f32 v[32:33], v[32:33], v[32:33]
	v_cvt_pk_bf16_f32 v18, v18, v19
	v_cvt_pk_bf16_f32 v19, v20, v21
	v_cvt_pk_bf16_f32 v20, v22, v23
	v_cvt_pk_bf16_f32 v21, v24, v25
	v_cvt_pk_bf16_f32 v22, v26, v27
	v_cvt_pk_bf16_f32 v23, v28, v29
	v_cvt_pk_bf16_f32 v24, v30, v31
	v_cvt_pk_bf16_f32 v25, v32, v33
	v_permlane16_swap_b32_e32 v18, v20
	v_permlane16_swap_b32_e32 v19, v21
	v_permlane16_swap_b32_e32 v22, v24
	v_permlane16_swap_b32_e32 v23, v25
	global_store_dwordx4 v[36:37], v[18:21], off nt
	global_store_dwordx4 v[36:37], v[22:25], off offset:256 nt
	s_nop 1
	v_mov_b32_e32 v18, v182
	s_and_b64 vcc, exec, s[4:5]
	v_fmamk_f32 v18, v18, 0x3a800000, v161
	v_mul_f32_e32 v19, 0x4b800000, v18
	v_cmp_gt_f32_e64 s[4:5], s53, v18
	s_nop 1
	v_cndmask_b32_e64 v18, v18, v19, s[4:5]
	v_rsq_f32_e32 v20, v18
	v_lshlrev_b64 v[18:19], 13, v[34:35]
	v_lshl_add_u64 v[18:19], s[10:11], 0, v[18:19]
	v_lshl_add_u64 v[18:19], v[18:19], 0, v[138:139]
	v_mul_f32_e32 v21, 0x45800000, v20
	v_cndmask_b32_e64 v20, v20, v21, s[4:5]
	v_mul_f32_e32 v14, v14, v20
	v_mul_f32_e32 v15, v15, v20
	v_mul_f32_e32 v16, v16, v20
	v_mul_f32_e32 v17, v17, v20
	v_mul_f32_e32 v10, v10, v20
	v_mul_f32_e32 v11, v11, v20
	v_mul_f32_e32 v12, v12, v20
	v_mul_f32_e32 v13, v13, v20
	v_mul_f32_e32 v21, v6, v20
	v_mul_f32_e32 v22, v7, v20
	v_mul_f32_e32 v23, v8, v20
	v_mul_f32_e32 v24, v9, v20
	v_mul_f32_e32 v25, v2, v20
	v_mul_f32_e32 v26, v3, v20
	v_mul_f32_e32 v27, v4, v20
	v_mul_f32_e32 v20, v5, v20
	v_max_f32_e32 v2, 0, v14
	v_max_f32_e32 v3, 0, v15
	v_max_f32_e32 v4, 0, v16
	v_max_f32_e32 v5, 0, v17
	v_max_f32_e32 v6, 0, v10
	v_max_f32_e32 v7, 0, v11
	v_max_f32_e32 v8, 0, v12
	v_max_f32_e32 v9, 0, v13
	v_max_f32_e32 v10, 0, v21
	v_max_f32_e32 v11, 0, v22
	v_max_f32_e32 v12, 0, v23
	v_max_f32_e32 v13, 0, v24
	v_max_f32_e32 v14, 0, v25
	v_max_f32_e32 v15, 0, v26
	v_max_f32_e32 v16, 0, v27
	v_max_f32_e32 v17, 0, v20
	v_pk_mul_f32 v[2:3], v[2:3], v[2:3]
	v_pk_mul_f32 v[4:5], v[4:5], v[4:5]
	v_pk_mul_f32 v[6:7], v[6:7], v[6:7]
	v_pk_mul_f32 v[8:9], v[8:9], v[8:9]
	v_pk_mul_f32 v[10:11], v[10:11], v[10:11]
	v_pk_mul_f32 v[12:13], v[12:13], v[12:13]
	v_pk_mul_f32 v[14:15], v[14:15], v[14:15]
	v_pk_mul_f32 v[16:17], v[16:17], v[16:17]
	v_cvt_pk_bf16_f32 v2, v2, v3
	v_cvt_pk_bf16_f32 v3, v4, v5
	v_cvt_pk_bf16_f32 v4, v6, v7
	v_cvt_pk_bf16_f32 v5, v8, v9
	v_cvt_pk_bf16_f32 v6, v10, v11
	v_cvt_pk_bf16_f32 v7, v12, v13
	v_cvt_pk_bf16_f32 v8, v14, v15
	v_cvt_pk_bf16_f32 v9, v16, v17
	v_permlane16_swap_b32_e32 v2, v4
	v_permlane16_swap_b32_e32 v3, v5
	v_permlane16_swap_b32_e32 v6, v8
	v_permlane16_swap_b32_e32 v7, v9
	global_store_dwordx4 v[18:19], v[2:5], off nt
	global_store_dwordx4 v[18:19], v[6:9], off offset:256 nt
	s_nop 1
	s_cbranch_vccz .LBB0_794
	s_waitcnt vmcnt(0)
	s_cmpk_gt_u32 s33, 0xff
	s_cbranch_scc1 .LBB0_804
	s_barrier
